# GEMM tile prologue also fetches the second K step's B fragments
# baseline (speedup 1.0000x reference)
.Lg2_ff2_nodma_1:
	s_add_u32 s58, s58, 0x800
	s_addc_u32 s59, s59, 0
	global_load_dwordx4 v[200:203], v160, s[58:59] offset:0
	global_load_dwordx4 v[204:207], v160, s[58:59] offset:1024
	global_load_dwordx4 v[208:211], v161, s[58:59] offset:0
	global_load_dwordx4 v[240:243], v161, s[58:59] offset:1024
	v_mov_b32_e32 v0, 0
	v_mov_b32_e32 v1, 0
	v_mov_b32_e32 v2, 0
	v_mov_b32_e32 v3, 0
	v_mov_b32_e32 v4, 0
	v_mov_b32_e32 v5, 0
	v_mov_b32_e32 v6, 0
	v_mov_b32_e32 v7, 0
	v_mov_b32_e32 v8, 0
	v_mov_b32_e32 v9, 0
	v_mov_b32_e32 v10, 0
	v_mov_b32_e32 v11, 0
	v_mov_b32_e32 v12, 0
	v_mov_b32_e32 v13, 0
	v_mov_b32_e32 v14, 0
	v_mov_b32_e32 v15, 0
	v_mov_b32_e32 v16, 0
	v_mov_b32_e32 v17, 0
	v_mov_b32_e32 v18, 0
	v_mov_b32_e32 v19, 0
	v_mov_b32_e32 v20, 0
	v_mov_b32_e32 v21, 0
	v_mov_b32_e32 v22, 0
	v_mov_b32_e32 v23, 0
	v_mov_b32_e32 v24, 0
	v_mov_b32_e32 v25, 0
	v_mov_b32_e32 v26, 0
	v_mov_b32_e32 v27, 0
	v_mov_b32_e32 v28, 0
	v_mov_b32_e32 v29, 0
	v_mov_b32_e32 v30, 0
	v_mov_b32_e32 v31, 0
	v_mov_b32_e32 v32, 0
	v_mov_b32_e32 v33, 0
	v_mov_b32_e32 v34, 0
	v_mov_b32_e32 v35, 0
	v_mov_b32_e32 v36, 0
	v_mov_b32_e32 v37, 0
	v_mov_b32_e32 v38, 0
	v_mov_b32_e32 v39, 0
	v_mov_b32_e32 v40, 0
	v_mov_b32_e32 v41, 0
	v_mov_b32_e32 v42, 0
	v_mov_b32_e32 v43, 0
	v_mov_b32_e32 v44, 0
	v_mov_b32_e32 v45, 0
	v_mov_b32_e32 v46, 0
	v_mov_b32_e32 v47, 0
	v_mov_b32_e32 v48, 0
	v_mov_b32_e32 v49, 0
	v_mov_b32_e32 v50, 0
	v_mov_b32_e32 v51, 0
	v_mov_b32_e32 v52, 0
	v_mov_b32_e32 v53, 0
	v_mov_b32_e32 v54, 0
	v_mov_b32_e32 v55, 0
	v_mov_b32_e32 v56, 0
	v_mov_b32_e32 v57, 0
	v_mov_b32_e32 v58, 0
	v_mov_b32_e32 v59, 0
	v_mov_b32_e32 v60, 0
	v_mov_b32_e32 v61, 0
	v_mov_b32_e32 v62, 0
	v_mov_b32_e32 v63, 0
	v_mov_b32_e32 v64, 0
	v_mov_b32_e32 v65, 0
	v_mov_b32_e32 v66, 0
	v_mov_b32_e32 v67, 0
	v_mov_b32_e32 v68, 0
	v_mov_b32_e32 v69, 0
	v_mov_b32_e32 v70, 0
	v_mov_b32_e32 v71, 0
	v_mov_b32_e32 v72, 0
	v_mov_b32_e32 v73, 0
	v_mov_b32_e32 v74, 0
	v_mov_b32_e32 v75, 0
	v_mov_b32_e32 v76, 0
	v_mov_b32_e32 v77, 0
	v_mov_b32_e32 v78, 0
	v_mov_b32_e32 v79, 0
	v_mov_b32_e32 v80, 0
	v_mov_b32_e32 v81, 0
	v_mov_b32_e32 v82, 0
	v_mov_b32_e32 v83, 0
	v_mov_b32_e32 v84, 0
	v_mov_b32_e32 v85, 0
	v_mov_b32_e32 v86, 0
	v_mov_b32_e32 v87, 0
	v_mov_b32_e32 v88, 0
	v_mov_b32_e32 v89, 0
	v_mov_b32_e32 v90, 0
	v_mov_b32_e32 v91, 0
	v_mov_b32_e32 v92, 0
	v_mov_b32_e32 v93, 0
	v_mov_b32_e32 v94, 0
	v_mov_b32_e32 v95, 0
	v_mov_b32_e32 v96, 0
	v_mov_b32_e32 v97, 0
	v_mov_b32_e32 v98, 0
	v_mov_b32_e32 v99, 0
	v_mov_b32_e32 v100, 0
	v_mov_b32_e32 v101, 0
	v_mov_b32_e32 v102, 0
	v_mov_b32_e32 v103, 0
	v_mov_b32_e32 v104, 0
	v_mov_b32_e32 v105, 0
	v_mov_b32_e32 v106, 0
	v_mov_b32_e32 v107, 0
	v_mov_b32_e32 v108, 0
	v_mov_b32_e32 v109, 0
	v_mov_b32_e32 v110, 0
	v_mov_b32_e32 v111, 0
	v_mov_b32_e32 v112, 0
	v_mov_b32_e32 v113, 0
	v_mov_b32_e32 v114, 0
	v_mov_b32_e32 v115, 0
	v_mov_b32_e32 v116, 0
	v_mov_b32_e32 v117, 0
	v_mov_b32_e32 v118, 0
	v_mov_b32_e32 v119, 0
	v_mov_b32_e32 v120, 0
	v_mov_b32_e32 v121, 0
	v_mov_b32_e32 v122, 0
	v_mov_b32_e32 v123, 0
	v_mov_b32_e32 v124, 0
	v_mov_b32_e32 v125, 0
	v_mov_b32_e32 v126, 0
	v_mov_b32_e32 v127, 0
	v_mov_b32_e32 v128, 0
	v_mov_b32_e32 v129, 0
	v_mov_b32_e32 v130, 0
	v_mov_b32_e32 v131, 0
	v_mov_b32_e32 v132, 0
	v_mov_b32_e32 v133, 0
	v_mov_b32_e32 v134, 0
	v_mov_b32_e32 v135, 0
	s_mov_b32 s63, 0
	s_waitcnt vmcnt(0)
	s_barrier
	ds_read_b128 v[136:139], v156 offset:0
	ds_read_b128 v[140:143], v156 offset:2048
	ds_read_b128 v[144:147], v156 offset:4096
	ds_read_b128 v[148:151], v156 offset:6144
	s_branch .Lg2_ff2_lin17

.Lg2_ff2_lin17:
	ds_read_b128 v[164:167], v156 offset:8192
	ds_read_b128 v[168:171], v156 offset:10240
	ds_read_b128 v[172:175], v156 offset:12288
	ds_read_b128 v[176:179], v156 offset:14336
	s_waitcnt lgkmcnt(4)
	v_mfma_f32_16x16x32_bf16 v[0:3], v[184:187], v[136:139], v[0:3]
	v_mfma_f32_16x16x32_bf16 v[4:7], v[192:195], v[136:139], v[4:7]
	v_mfma_f32_16x16x32_bf16 v[8:11], v[184:187], v[140:143], v[8:11]
	v_mfma_f32_16x16x32_bf16 v[12:15], v[192:195], v[140:143], v[12:15]
	v_mfma_f32_16x16x32_bf16 v[16:19], v[184:187], v[144:147], v[16:19]
	v_mfma_f32_16x16x32_bf16 v[20:23], v[192:195], v[144:147], v[20:23]
	v_mfma_f32_16x16x32_bf16 v[24:27], v[184:187], v[148:151], v[24:27]
	v_mfma_f32_16x16x32_bf16 v[28:31], v[192:195], v[148:151], v[28:31]
	ds_read_b128 v[136:139], v156 offset:16384
	ds_read_b128 v[140:143], v156 offset:18432
	ds_read_b128 v[144:147], v156 offset:20480
	ds_read_b128 v[148:151], v156 offset:22528
	s_waitcnt lgkmcnt(4)
	v_mfma_f32_16x16x32_bf16 v[32:35], v[184:187], v[164:167], v[32:35]
	v_mfma_f32_16x16x32_bf16 v[36:39], v[192:195], v[164:167], v[36:39]
	v_mfma_f32_16x16x32_bf16 v[40:43], v[184:187], v[168:171], v[40:43]
	v_mfma_f32_16x16x32_bf16 v[44:47], v[192:195], v[168:171], v[44:47]
	v_mfma_f32_16x16x32_bf16 v[48:51], v[184:187], v[172:175], v[48:51]
	v_mfma_f32_16x16x32_bf16 v[52:55], v[192:195], v[172:175], v[52:55]
	v_mfma_f32_16x16x32_bf16 v[56:59], v[184:187], v[176:179], v[56:59]
	v_mfma_f32_16x16x32_bf16 v[60:63], v[192:195], v[176:179], v[60:63]
	ds_read_b128 v[164:167], v156 offset:24576
	ds_read_b128 v[168:171], v156 offset:26624
	ds_read_b128 v[172:175], v156 offset:28672
	ds_read_b128 v[176:179], v156 offset:30720
	ds_read_b128 v[180:183], v156 offset:32768
	s_waitcnt lgkmcnt(5)
	v_mfma_f32_16x16x32_bf16 v[64:67], v[184:187], v[136:139], v[64:67]
	v_mfma_f32_16x16x32_bf16 v[68:71], v[192:195], v[136:139], v[68:71]
	v_mfma_f32_16x16x32_bf16 v[72:75], v[184:187], v[140:143], v[72:75]
	v_mfma_f32_16x16x32_bf16 v[76:79], v[192:195], v[140:143], v[76:79]
	v_mfma_f32_16x16x32_bf16 v[80:83], v[184:187], v[144:147], v[80:83]
	v_mfma_f32_16x16x32_bf16 v[84:87], v[192:195], v[144:147], v[84:87]
	v_mfma_f32_16x16x32_bf16 v[88:91], v[184:187], v[148:151], v[88:91]
	v_mfma_f32_16x16x32_bf16 v[92:95], v[192:195], v[148:151], v[92:95]
	ds_read_b128 v[136:139], v157 offset:0
	ds_read_b128 v[140:143], v157 offset:2048
	ds_read_b128 v[144:147], v157 offset:4096
	ds_read_b128 v[148:151], v157 offset:6144
	s_waitcnt lgkmcnt(4)
	v_mfma_f32_16x16x32_bf16 v[96:99], v[184:187], v[164:167], v[96:99]
	v_mfma_f32_16x16x32_bf16 v[100:103], v[192:195], v[164:167], v[100:103]
	v_mfma_f32_16x16x32_bf16 v[104:107], v[184:187], v[168:171], v[104:107]
	v_mfma_f32_16x16x32_bf16 v[108:111], v[192:195], v[168:171], v[108:111]
	v_mfma_f32_16x16x32_bf16 v[112:115], v[184:187], v[172:175], v[112:115]
	v_mfma_f32_16x16x32_bf16 v[116:119], v[192:195], v[172:175], v[116:119]
	v_mfma_f32_16x16x32_bf16 v[120:123], v[184:187], v[176:179], v[120:123]
	v_mfma_f32_16x16x32_bf16 v[124:127], v[192:195], v[176:179], v[124:127]
	v_mfma_f32_16x16x32_bf16 v[128:131], v[184:187], v[180:183], v[128:131]
	v_mfma_f32_16x16x32_bf16 v[132:135], v[192:195], v[180:183], v[132:135]
	ds_read_b128 v[164:167], v157 offset:8192
	ds_read_b128 v[168:171], v157 offset:10240
	ds_read_b128 v[172:175], v157 offset:12288
	ds_read_b128 v[176:179], v157 offset:14336
	s_waitcnt lgkmcnt(4)
	v_mfma_f32_16x16x32_bf16 v[0:3], v[188:191], v[136:139], v[0:3]
	v_mfma_f32_16x16x32_bf16 v[4:7], v[196:199], v[136:139], v[4:7]
	v_mfma_f32_16x16x32_bf16 v[8:11], v[188:191], v[140:143], v[8:11]
	v_mfma_f32_16x16x32_bf16 v[12:15], v[196:199], v[140:143], v[12:15]
	v_mfma_f32_16x16x32_bf16 v[16:19], v[188:191], v[144:147], v[16:19]
	v_mfma_f32_16x16x32_bf16 v[20:23], v[196:199], v[144:147], v[20:23]
	v_mfma_f32_16x16x32_bf16 v[24:27], v[188:191], v[148:151], v[24:27]
	v_mfma_f32_16x16x32_bf16 v[28:31], v[196:199], v[148:151], v[28:31]
	ds_read_b128 v[136:139], v157 offset:16384
	ds_read_b128 v[140:143], v157 offset:18432
	ds_read_b128 v[144:147], v157 offset:20480
	ds_read_b128 v[148:151], v157 offset:22528
	s_waitcnt lgkmcnt(4)
	v_mfma_f32_16x16x32_bf16 v[32:35], v[188:191], v[164:167], v[32:35]
	v_mfma_f32_16x16x32_bf16 v[36:39], v[196:199], v[164:167], v[36:39]
	v_mfma_f32_16x16x32_bf16 v[40:43], v[188:191], v[168:171], v[40:43]
	v_mfma_f32_16x16x32_bf16 v[44:47], v[196:199], v[168:171], v[44:47]
	v_mfma_f32_16x16x32_bf16 v[48:51], v[188:191], v[172:175], v[48:51]
	v_mfma_f32_16x16x32_bf16 v[52:55], v[196:199], v[172:175], v[52:55]
	v_mfma_f32_16x16x32_bf16 v[56:59], v[188:191], v[176:179], v[56:59]
	v_mfma_f32_16x16x32_bf16 v[60:63], v[196:199], v[176:179], v[60:63]
	ds_read_b128 v[164:167], v157 offset:24576
	ds_read_b128 v[168:171], v157 offset:26624
	ds_read_b128 v[172:175], v157 offset:28672
	ds_read_b128 v[176:179], v157 offset:30720
	ds_read_b128 v[180:183], v157 offset:32768
	s_waitcnt lgkmcnt(5)
	v_mfma_f32_16x16x32_bf16 v[64:67], v[188:191], v[136:139], v[64:67]
	v_mfma_f32_16x16x32_bf16 v[68:71], v[196:199], v[136:139], v[68:71]
	v_mfma_f32_16x16x32_bf16 v[72:75], v[188:191], v[140:143], v[72:75]
	v_mfma_f32_16x16x32_bf16 v[76:79], v[196:199], v[140:143], v[76:79]
	v_mfma_f32_16x16x32_bf16 v[80:83], v[188:191], v[144:147], v[80:83]
	v_mfma_f32_16x16x32_bf16 v[84:87], v[196:199], v[144:147], v[84:87]
	v_mfma_f32_16x16x32_bf16 v[88:91], v[188:191], v[148:151], v[88:91]
	v_mfma_f32_16x16x32_bf16 v[92:95], v[196:199], v[148:151], v[92:95]
	s_waitcnt vmcnt(0) lgkmcnt(0)
	s_barrier
	s_cmp_ge_u32 s63, 62
	s_cbranch_scc1 .Lg2_ff2_nd17_0
	s_add_u32 s56, s56, 0x80
	s_addc_u32 s57, s57, 0
	s_add_u32 m0, s62, 0x0
	s_add_u32 s4, s56, 0x0
	s_addc_u32 s5, s57, 0
	global_load_lds_dwordx4 v162, s[4:5]
	s_add_u32 m0, s62, 0x1000
	s_add_u32 s4, s56, 0x40000
	s_addc_u32 s5, s57, 0
	global_load_lds_dwordx4 v162, s[4:5]
	s_add_u32 m0, s62, 0x2000
	s_add_u32 s4, s56, 0x80000
	s_addc_u32 s5, s57, 0
	global_load_lds_dwordx4 v162, s[4:5]
	s_add_u32 m0, s62, 0x3000
	s_add_u32 s4, s56, 0xc0000
	s_addc_u32 s5, s57, 0
	global_load_lds_dwordx4 v162, s[4:5]
	s_add_u32 m0, s62, 0x4000
	s_add_u32 s4, s56, 0x100000
	s_addc_u32 s5, s57, 0
	global_load_lds_dwordx4 v162, s[4:5]
	s_add_u32 m0, s62, 0x5000
	s_add_u32 s4, s56, 0x140000
	s_addc_u32 s5, s57, 0
	global_load_lds_dwordx4 v162, s[4:5]
	s_add_u32 m0, s62, 0x6000
	s_add_u32 s4, s56, 0x180000
	s_addc_u32 s5, s57, 0
	global_load_lds_dwordx4 v162, s[4:5]
	s_add_u32 m0, s62, 0x7000
	s_add_u32 s4, s56, 0x1c0000
	s_addc_u32 s5, s57, 0
	global_load_lds_dwordx4 v162, s[4:5]
	s_cmp_gt_u32 s70, 1
	s_cbranch_scc1 .Lg2_ff2_nodma_2
	s_add_u32 m0, s62, 0x8000
	s_add_u32 s4, s56, 0x200000
	s_addc_u32 s5, s57, 0
	global_load_lds_dwordx4 v162, s[4:5]

.Lg2_ff2_k16:
	s_add_u32 m0, s62, 0x0
	s_add_u32 s4, s56, 0x0
	s_addc_u32 s5, s57, 0
	global_load_lds_dwordx4 v162, s[4:5]
	s_add_u32 m0, s62, 0x1000
	s_add_u32 s4, s56, 0x40000
	s_addc_u32 s5, s57, 0
	global_load_lds_dwordx4 v162, s[4:5]
	s_add_u32 m0, s62, 0x2000
	s_add_u32 s4, s56, 0x80000
	s_addc_u32 s5, s57, 0
	global_load_lds_dwordx4 v162, s[4:5]
	s_add_u32 m0, s62, 0x3000
	s_add_u32 s4, s56, 0xc0000
	s_addc_u32 s5, s57, 0
	global_load_lds_dwordx4 v162, s[4:5]
	s_add_u32 m0, s62, 0x4000
	s_add_u32 s4, s56, 0x100000
	s_addc_u32 s5, s57, 0
	global_load_lds_dwordx4 v162, s[4:5]
	s_add_u32 m0, s62, 0x5000
	s_add_u32 s4, s56, 0x140000
	s_addc_u32 s5, s57, 0
	global_load_lds_dwordx4 v162, s[4:5]
	s_add_u32 m0, s62, 0x6000
	s_add_u32 s4, s56, 0x180000
	s_addc_u32 s5, s57, 0
	global_load_lds_dwordx4 v162, s[4:5]
	s_add_u32 m0, s62, 0x7000
	s_add_u32 s4, s56, 0x1c0000
	s_addc_u32 s5, s57, 0
	global_load_lds_dwordx4 v162, s[4:5]
	global_load_dwordx4 v[184:187], v160, s[58:59] offset:0
	global_load_dwordx4 v[188:191], v160, s[58:59] offset:1024
	global_load_dwordx4 v[192:195], v161, s[58:59] offset:0
	global_load_dwordx4 v[196:199], v161, s[58:59] offset:1024
	s_add_u32 s56, s56, 0x80
	s_addc_u32 s57, s57, 0
	s_add_u32 m0, s62, 0x8800
	s_add_u32 s4, s56, 0x0
	s_addc_u32 s5, s57, 0
	global_load_lds_dwordx4 v162, s[4:5]
	s_add_u32 m0, s62, 0x9800
	s_add_u32 s4, s56, 0x40000
	s_addc_u32 s5, s57, 0
	global_load_lds_dwordx4 v162, s[4:5]
	s_add_u32 m0, s62, 0xa800
	s_add_u32 s4, s56, 0x80000
	s_addc_u32 s5, s57, 0
	global_load_lds_dwordx4 v162, s[4:5]
	s_add_u32 m0, s62, 0xb800
	s_add_u32 s4, s56, 0xc0000
	s_addc_u32 s5, s57, 0
	global_load_lds_dwordx4 v162, s[4:5]
	s_add_u32 m0, s62, 0xc800
	s_add_u32 s4, s56, 0x100000
	s_addc_u32 s5, s57, 0
	global_load_lds_dwordx4 v162, s[4:5]
	s_add_u32 m0, s62, 0xd800
	s_add_u32 s4, s56, 0x140000
	s_addc_u32 s5, s57, 0
	global_load_lds_dwordx4 v162, s[4:5]
	s_add_u32 m0, s62, 0xe800
	s_add_u32 s4, s56, 0x180000
	s_addc_u32 s5, s57, 0
	global_load_lds_dwordx4 v162, s[4:5]
	s_add_u32 m0, s62, 0xf800
	s_add_u32 s4, s56, 0x1c0000
	s_addc_u32 s5, s57, 0
	global_load_lds_dwordx4 v162, s[4:5]
	s_add_u32 s58, s58, 0x800
	s_addc_u32 s59, s59, 0
	global_load_dwordx4 v[200:203], v160, s[58:59] offset:0
	global_load_dwordx4 v[204:207], v160, s[58:59] offset:1024
	global_load_dwordx4 v[208:211], v161, s[58:59] offset:0
	global_load_dwordx4 v[240:243], v161, s[58:59] offset:1024
	v_mov_b32_e32 v0, 0
	v_mov_b32_e32 v1, 0
	v_mov_b32_e32 v2, 0
	v_mov_b32_e32 v3, 0
	v_mov_b32_e32 v4, 0
	v_mov_b32_e32 v5, 0
	v_mov_b32_e32 v6, 0
	v_mov_b32_e32 v7, 0
	v_mov_b32_e32 v8, 0
	v_mov_b32_e32 v9, 0
	v_mov_b32_e32 v10, 0
	v_mov_b32_e32 v11, 0
	v_mov_b32_e32 v12, 0
	v_mov_b32_e32 v13, 0
	v_mov_b32_e32 v14, 0
	v_mov_b32_e32 v15, 0
	v_mov_b32_e32 v16, 0
	v_mov_b32_e32 v17, 0
	v_mov_b32_e32 v18, 0
	v_mov_b32_e32 v19, 0
	v_mov_b32_e32 v20, 0
	v_mov_b32_e32 v21, 0
	v_mov_b32_e32 v22, 0
	v_mov_b32_e32 v23, 0
	v_mov_b32_e32 v24, 0
	v_mov_b32_e32 v25, 0
	v_mov_b32_e32 v26, 0
	v_mov_b32_e32 v27, 0
	v_mov_b32_e32 v28, 0
	v_mov_b32_e32 v29, 0
	v_mov_b32_e32 v30, 0
	v_mov_b32_e32 v31, 0
	v_mov_b32_e32 v32, 0
	v_mov_b32_e32 v33, 0
	v_mov_b32_e32 v34, 0
	v_mov_b32_e32 v35, 0
	v_mov_b32_e32 v36, 0
	v_mov_b32_e32 v37, 0
	v_mov_b32_e32 v38, 0
	v_mov_b32_e32 v39, 0
	v_mov_b32_e32 v40, 0
	v_mov_b32_e32 v41, 0
	v_mov_b32_e32 v42, 0
	v_mov_b32_e32 v43, 0
	v_mov_b32_e32 v44, 0
	v_mov_b32_e32 v45, 0
	v_mov_b32_e32 v46, 0
	v_mov_b32_e32 v47, 0
	v_mov_b32_e32 v48, 0
	v_mov_b32_e32 v49, 0
	v_mov_b32_e32 v50, 0
	v_mov_b32_e32 v51, 0
	v_mov_b32_e32 v52, 0
	v_mov_b32_e32 v53, 0
	v_mov_b32_e32 v54, 0
	v_mov_b32_e32 v55, 0
	v_mov_b32_e32 v56, 0
	v_mov_b32_e32 v57, 0
	v_mov_b32_e32 v58, 0
	v_mov_b32_e32 v59, 0
	v_mov_b32_e32 v60, 0
	v_mov_b32_e32 v61, 0
	v_mov_b32_e32 v62, 0
	v_mov_b32_e32 v63, 0
	v_mov_b32_e32 v64, 0
	v_mov_b32_e32 v65, 0
	v_mov_b32_e32 v66, 0
	v_mov_b32_e32 v67, 0
	v_mov_b32_e32 v68, 0
	v_mov_b32_e32 v69, 0
	v_mov_b32_e32 v70, 0
	v_mov_b32_e32 v71, 0
	v_mov_b32_e32 v72, 0
	v_mov_b32_e32 v73, 0
	v_mov_b32_e32 v74, 0
	v_mov_b32_e32 v75, 0
	v_mov_b32_e32 v76, 0
	v_mov_b32_e32 v77, 0
	v_mov_b32_e32 v78, 0
	v_mov_b32_e32 v79, 0
	v_mov_b32_e32 v80, 0
	v_mov_b32_e32 v81, 0
	v_mov_b32_e32 v82, 0
	v_mov_b32_e32 v83, 0
	v_mov_b32_e32 v84, 0
	v_mov_b32_e32 v85, 0
	v_mov_b32_e32 v86, 0
	v_mov_b32_e32 v87, 0
	v_mov_b32_e32 v88, 0
	v_mov_b32_e32 v89, 0
	v_mov_b32_e32 v90, 0
	v_mov_b32_e32 v91, 0
	v_mov_b32_e32 v92, 0
	v_mov_b32_e32 v93, 0
	v_mov_b32_e32 v94, 0
	v_mov_b32_e32 v95, 0
	v_mov_b32_e32 v96, 0
	v_mov_b32_e32 v97, 0
	v_mov_b32_e32 v98, 0
	v_mov_b32_e32 v99, 0
	v_mov_b32_e32 v100, 0
	v_mov_b32_e32 v101, 0
	v_mov_b32_e32 v102, 0
	v_mov_b32_e32 v103, 0
	v_mov_b32_e32 v104, 0
	v_mov_b32_e32 v105, 0
	v_mov_b32_e32 v106, 0
	v_mov_b32_e32 v107, 0
	v_mov_b32_e32 v108, 0
	v_mov_b32_e32 v109, 0
	v_mov_b32_e32 v110, 0
	v_mov_b32_e32 v111, 0
	v_mov_b32_e32 v112, 0
	v_mov_b32_e32 v113, 0
	v_mov_b32_e32 v114, 0
	v_mov_b32_e32 v115, 0
	v_mov_b32_e32 v116, 0
	v_mov_b32_e32 v117, 0
	v_mov_b32_e32 v118, 0
	v_mov_b32_e32 v119, 0
	v_mov_b32_e32 v120, 0
	v_mov_b32_e32 v121, 0
	v_mov_b32_e32 v122, 0
	v_mov_b32_e32 v123, 0
	v_mov_b32_e32 v124, 0
	v_mov_b32_e32 v125, 0
	v_mov_b32_e32 v126, 0
	v_mov_b32_e32 v127, 0
	s_mov_b32 s63, 0
	s_waitcnt vmcnt(0)
	s_barrier
	ds_read_b128 v[136:139], v156 offset:0
	ds_read_b128 v[140:143], v156 offset:2048
	ds_read_b128 v[144:147], v156 offset:4096
	ds_read_b128 v[148:151], v156 offset:6144
	s_branch .Lg2_ff2_lin16

.Lg2_ff2_lin16:
	ds_read_b128 v[164:167], v156 offset:8192
	ds_read_b128 v[168:171], v156 offset:10240
	ds_read_b128 v[172:175], v156 offset:12288
	ds_read_b128 v[176:179], v156 offset:14336
	s_waitcnt lgkmcnt(4)
	v_mfma_f32_16x16x32_bf16 v[0:3], v[184:187], v[136:139], v[0:3]
	v_mfma_f32_16x16x32_bf16 v[4:7], v[192:195], v[136:139], v[4:7]
	v_mfma_f32_16x16x32_bf16 v[8:11], v[184:187], v[140:143], v[8:11]
	v_mfma_f32_16x16x32_bf16 v[12:15], v[192:195], v[140:143], v[12:15]
	v_mfma_f32_16x16x32_bf16 v[16:19], v[184:187], v[144:147], v[16:19]
	v_mfma_f32_16x16x32_bf16 v[20:23], v[192:195], v[144:147], v[20:23]
	v_mfma_f32_16x16x32_bf16 v[24:27], v[184:187], v[148:151], v[24:27]
	v_mfma_f32_16x16x32_bf16 v[28:31], v[192:195], v[148:151], v[28:31]
	ds_read_b128 v[136:139], v156 offset:16384
	ds_read_b128 v[140:143], v156 offset:18432
	ds_read_b128 v[144:147], v156 offset:20480
	ds_read_b128 v[148:151], v156 offset:22528
	s_waitcnt lgkmcnt(4)
	v_mfma_f32_16x16x32_bf16 v[32:35], v[184:187], v[164:167], v[32:35]
	v_mfma_f32_16x16x32_bf16 v[36:39], v[192:195], v[164:167], v[36:39]
	v_mfma_f32_16x16x32_bf16 v[40:43], v[184:187], v[168:171], v[40:43]
	v_mfma_f32_16x16x32_bf16 v[44:47], v[192:195], v[168:171], v[44:47]
	v_mfma_f32_16x16x32_bf16 v[48:51], v[184:187], v[172:175], v[48:51]
	v_mfma_f32_16x16x32_bf16 v[52:55], v[192:195], v[172:175], v[52:55]
	v_mfma_f32_16x16x32_bf16 v[56:59], v[184:187], v[176:179], v[56:59]
	v_mfma_f32_16x16x32_bf16 v[60:63], v[192:195], v[176:179], v[60:63]
	ds_read_b128 v[164:167], v156 offset:24576
	ds_read_b128 v[168:171], v156 offset:26624
	ds_read_b128 v[172:175], v156 offset:28672
	ds_read_b128 v[176:179], v156 offset:30720
	s_waitcnt lgkmcnt(4)
	v_mfma_f32_16x16x32_bf16 v[64:67], v[184:187], v[136:139], v[64:67]
	v_mfma_f32_16x16x32_bf16 v[68:71], v[192:195], v[136:139], v[68:71]
	v_mfma_f32_16x16x32_bf16 v[72:75], v[184:187], v[140:143], v[72:75]
	v_mfma_f32_16x16x32_bf16 v[76:79], v[192:195], v[140:143], v[76:79]
	v_mfma_f32_16x16x32_bf16 v[80:83], v[184:187], v[144:147], v[80:83]
	v_mfma_f32_16x16x32_bf16 v[84:87], v[192:195], v[144:147], v[84:87]
	v_mfma_f32_16x16x32_bf16 v[88:91], v[184:187], v[148:151], v[88:91]
	v_mfma_f32_16x16x32_bf16 v[92:95], v[192:195], v[148:151], v[92:95]
	ds_read_b128 v[136:139], v157 offset:0
	ds_read_b128 v[140:143], v157 offset:2048
	ds_read_b128 v[144:147], v157 offset:4096
	ds_read_b128 v[148:151], v157 offset:6144
	s_waitcnt lgkmcnt(4)
	v_mfma_f32_16x16x32_bf16 v[96:99], v[184:187], v[164:167], v[96:99]
	v_mfma_f32_16x16x32_bf16 v[100:103], v[192:195], v[164:167], v[100:103]
	v_mfma_f32_16x16x32_bf16 v[104:107], v[184:187], v[168:171], v[104:107]
	v_mfma_f32_16x16x32_bf16 v[108:111], v[192:195], v[168:171], v[108:111]
	v_mfma_f32_16x16x32_bf16 v[112:115], v[184:187], v[172:175], v[112:115]
	v_mfma_f32_16x16x32_bf16 v[116:119], v[192:195], v[172:175], v[116:119]
	v_mfma_f32_16x16x32_bf16 v[120:123], v[184:187], v[176:179], v[120:123]
	v_mfma_f32_16x16x32_bf16 v[124:127], v[192:195], v[176:179], v[124:127]
	ds_read_b128 v[164:167], v157 offset:8192
	ds_read_b128 v[168:171], v157 offset:10240
	ds_read_b128 v[172:175], v157 offset:12288
	ds_read_b128 v[176:179], v157 offset:14336
	s_waitcnt lgkmcnt(4)
	v_mfma_f32_16x16x32_bf16 v[0:3], v[188:191], v[136:139], v[0:3]
	v_mfma_f32_16x16x32_bf16 v[4:7], v[196:199], v[136:139], v[4:7]
	v_mfma_f32_16x16x32_bf16 v[8:11], v[188:191], v[140:143], v[8:11]
	v_mfma_f32_16x16x32_bf16 v[12:15], v[196:199], v[140:143], v[12:15]
	v_mfma_f32_16x16x32_bf16 v[16:19], v[188:191], v[144:147], v[16:19]
	v_mfma_f32_16x16x32_bf16 v[20:23], v[196:199], v[144:147], v[20:23]
	v_mfma_f32_16x16x32_bf16 v[24:27], v[188:191], v[148:151], v[24:27]
	v_mfma_f32_16x16x32_bf16 v[28:31], v[196:199], v[148:151], v[28:31]
	ds_read_b128 v[136:139], v157 offset:16384
	ds_read_b128 v[140:143], v157 offset:18432
	ds_read_b128 v[144:147], v157 offset:20480
	ds_read_b128 v[148:151], v157 offset:22528
	s_waitcnt lgkmcnt(4)
	v_mfma_f32_16x16x32_bf16 v[32:35], v[188:191], v[164:167], v[32:35]
	v_mfma_f32_16x16x32_bf16 v[36:39], v[196:199], v[164:167], v[36:39]
	v_mfma_f32_16x16x32_bf16 v[40:43], v[188:191], v[168:171], v[40:43]
	v_mfma_f32_16x16x32_bf16 v[44:47], v[196:199], v[168:171], v[44:47]
	v_mfma_f32_16x16x32_bf16 v[48:51], v[188:191], v[172:175], v[48:51]
	v_mfma_f32_16x16x32_bf16 v[52:55], v[196:199], v[172:175], v[52:55]
	v_mfma_f32_16x16x32_bf16 v[56:59], v[188:191], v[176:179], v[56:59]
	v_mfma_f32_16x16x32_bf16 v[60:63], v[196:199], v[176:179], v[60:63]
	ds_read_b128 v[164:167], v157 offset:24576
	ds_read_b128 v[168:171], v157 offset:26624
	ds_read_b128 v[172:175], v157 offset:28672
	ds_read_b128 v[176:179], v157 offset:30720
	s_waitcnt lgkmcnt(4)
	v_mfma_f32_16x16x32_bf16 v[64:67], v[188:191], v[136:139], v[64:67]
	v_mfma_f32_16x16x32_bf16 v[68:71], v[196:199], v[136:139], v[68:71]
	v_mfma_f32_16x16x32_bf16 v[72:75], v[188:191], v[140:143], v[72:75]
	v_mfma_f32_16x16x32_bf16 v[76:79], v[196:199], v[140:143], v[76:79]
	v_mfma_f32_16x16x32_bf16 v[80:83], v[188:191], v[144:147], v[80:83]
	v_mfma_f32_16x16x32_bf16 v[84:87], v[196:199], v[144:147], v[84:87]
	v_mfma_f32_16x16x32_bf16 v[88:91], v[188:191], v[148:151], v[88:91]
	v_mfma_f32_16x16x32_bf16 v[92:95], v[196:199], v[148:151], v[92:95]
	s_waitcnt vmcnt(0) lgkmcnt(0)
	s_barrier
	s_cmp_ge_u32 s63, 62
	s_cbranch_scc1 .Lg2_ff2_nd16_0
	s_add_u32 s56, s56, 0x80
	s_addc_u32 s57, s57, 0
	s_add_u32 m0, s62, 0x0
	s_add_u32 s4, s56, 0x0
	s_addc_u32 s5, s57, 0
	global_load_lds_dwordx4 v162, s[4:5]
	s_add_u32 m0, s62, 0x1000
	s_add_u32 s4, s56, 0x40000
	s_addc_u32 s5, s57, 0
	global_load_lds_dwordx4 v162, s[4:5]
	s_add_u32 m0, s62, 0x2000
	s_add_u32 s4, s56, 0x80000
	s_addc_u32 s5, s57, 0
	global_load_lds_dwordx4 v162, s[4:5]
	s_add_u32 m0, s62, 0x3000
	s_add_u32 s4, s56, 0xc0000
	s_addc_u32 s5, s57, 0
	global_load_lds_dwordx4 v162, s[4:5]
	s_add_u32 m0, s62, 0x4000
	s_add_u32 s4, s56, 0x100000
	s_addc_u32 s5, s57, 0
	global_load_lds_dwordx4 v162, s[4:5]
	s_add_u32 m0, s62, 0x5000
	s_add_u32 s4, s56, 0x140000
	s_addc_u32 s5, s57, 0
	global_load_lds_dwordx4 v162, s[4:5]
	s_add_u32 m0, s62, 0x6000
	s_add_u32 s4, s56, 0x180000
	s_addc_u32 s5, s57, 0
	global_load_lds_dwordx4 v162, s[4:5]
	s_add_u32 m0, s62, 0x7000
	s_add_u32 s4, s56, 0x1c0000
	s_addc_u32 s5, s57, 0
	global_load_lds_dwordx4 v162, s[4:5]

.Lg2_ff1_lin17:
	ds_read_b128 v[164:167], v156 offset:8192
	ds_read_b128 v[168:171], v156 offset:10240
	ds_read_b128 v[172:175], v156 offset:12288
	ds_read_b128 v[176:179], v156 offset:14336
	s_waitcnt lgkmcnt(4)
	v_mfma_f32_16x16x32_bf16 v[0:3], v[184:187], v[136:139], v[0:3]
	v_mfma_f32_16x16x32_bf16 v[4:7], v[192:195], v[136:139], v[4:7]
	v_mfma_f32_16x16x32_bf16 v[8:11], v[184:187], v[140:143], v[8:11]
	v_mfma_f32_16x16x32_bf16 v[12:15], v[192:195], v[140:143], v[12:15]
	v_mfma_f32_16x16x32_bf16 v[16:19], v[184:187], v[144:147], v[16:19]
	v_mfma_f32_16x16x32_bf16 v[20:23], v[192:195], v[144:147], v[20:23]
	v_mfma_f32_16x16x32_bf16 v[24:27], v[184:187], v[148:151], v[24:27]
	v_mfma_f32_16x16x32_bf16 v[28:31], v[192:195], v[148:151], v[28:31]
	ds_read_b128 v[136:139], v156 offset:16384
	ds_read_b128 v[140:143], v156 offset:18432
	ds_read_b128 v[144:147], v156 offset:20480
	ds_read_b128 v[148:151], v156 offset:22528
	s_waitcnt lgkmcnt(4)
	v_mfma_f32_16x16x32_bf16 v[32:35], v[184:187], v[164:167], v[32:35]
	v_mfma_f32_16x16x32_bf16 v[36:39], v[192:195], v[164:167], v[36:39]
	v_mfma_f32_16x16x32_bf16 v[40:43], v[184:187], v[168:171], v[40:43]
	v_mfma_f32_16x16x32_bf16 v[44:47], v[192:195], v[168:171], v[44:47]
	v_mfma_f32_16x16x32_bf16 v[48:51], v[184:187], v[172:175], v[48:51]
	v_mfma_f32_16x16x32_bf16 v[52:55], v[192:195], v[172:175], v[52:55]
	v_mfma_f32_16x16x32_bf16 v[56:59], v[184:187], v[176:179], v[56:59]
	v_mfma_f32_16x16x32_bf16 v[60:63], v[192:195], v[176:179], v[60:63]
	ds_read_b128 v[164:167], v156 offset:24576
	ds_read_b128 v[168:171], v156 offset:26624
	ds_read_b128 v[172:175], v156 offset:28672
	ds_read_b128 v[176:179], v156 offset:30720
	ds_read_b128 v[180:183], v156 offset:32768
	s_waitcnt lgkmcnt(5)
	v_mfma_f32_16x16x32_bf16 v[64:67], v[184:187], v[136:139], v[64:67]
	v_mfma_f32_16x16x32_bf16 v[68:71], v[192:195], v[136:139], v[68:71]
	v_mfma_f32_16x16x32_bf16 v[72:75], v[184:187], v[140:143], v[72:75]
	v_mfma_f32_16x16x32_bf16 v[76:79], v[192:195], v[140:143], v[76:79]
	v_mfma_f32_16x16x32_bf16 v[80:83], v[184:187], v[144:147], v[80:83]
	v_mfma_f32_16x16x32_bf16 v[84:87], v[192:195], v[144:147], v[84:87]
	v_mfma_f32_16x16x32_bf16 v[88:91], v[184:187], v[148:151], v[88:91]
	v_mfma_f32_16x16x32_bf16 v[92:95], v[192:195], v[148:151], v[92:95]
	ds_read_b128 v[136:139], v157 offset:0
	ds_read_b128 v[140:143], v157 offset:2048
	ds_read_b128 v[144:147], v157 offset:4096
	ds_read_b128 v[148:151], v157 offset:6144
	s_waitcnt lgkmcnt(4)
	v_mfma_f32_16x16x32_bf16 v[96:99], v[184:187], v[164:167], v[96:99]
	v_mfma_f32_16x16x32_bf16 v[100:103], v[192:195], v[164:167], v[100:103]
	v_mfma_f32_16x16x32_bf16 v[104:107], v[184:187], v[168:171], v[104:107]
	v_mfma_f32_16x16x32_bf16 v[108:111], v[192:195], v[168:171], v[108:111]
	v_mfma_f32_16x16x32_bf16 v[112:115], v[184:187], v[172:175], v[112:115]
	v_mfma_f32_16x16x32_bf16 v[116:119], v[192:195], v[172:175], v[116:119]
	v_mfma_f32_16x16x32_bf16 v[120:123], v[184:187], v[176:179], v[120:123]
	v_mfma_f32_16x16x32_bf16 v[124:127], v[192:195], v[176:179], v[124:127]
	v_mfma_f32_16x16x32_bf16 v[128:131], v[184:187], v[180:183], v[128:131]
	v_mfma_f32_16x16x32_bf16 v[132:135], v[192:195], v[180:183], v[132:135]
	ds_read_b128 v[164:167], v157 offset:8192
	ds_read_b128 v[168:171], v157 offset:10240
	ds_read_b128 v[172:175], v157 offset:12288
	ds_read_b128 v[176:179], v157 offset:14336
	s_waitcnt lgkmcnt(4)
	v_mfma_f32_16x16x32_bf16 v[0:3], v[188:191], v[136:139], v[0:3]
	v_mfma_f32_16x16x32_bf16 v[4:7], v[196:199], v[136:139], v[4:7]
	v_mfma_f32_16x16x32_bf16 v[8:11], v[188:191], v[140:143], v[8:11]
	v_mfma_f32_16x16x32_bf16 v[12:15], v[196:199], v[140:143], v[12:15]
	v_mfma_f32_16x16x32_bf16 v[16:19], v[188:191], v[144:147], v[16:19]
	v_mfma_f32_16x16x32_bf16 v[20:23], v[196:199], v[144:147], v[20:23]
	v_mfma_f32_16x16x32_bf16 v[24:27], v[188:191], v[148:151], v[24:27]
	v_mfma_f32_16x16x32_bf16 v[28:31], v[196:199], v[148:151], v[28:31]
	ds_read_b128 v[136:139], v157 offset:16384
	ds_read_b128 v[140:143], v157 offset:18432
	ds_read_b128 v[144:147], v157 offset:20480
	ds_read_b128 v[148:151], v157 offset:22528
	s_waitcnt lgkmcnt(4)
	v_mfma_f32_16x16x32_bf16 v[32:35], v[188:191], v[164:167], v[32:35]
	v_mfma_f32_16x16x32_bf16 v[36:39], v[196:199], v[164:167], v[36:39]
	v_mfma_f32_16x16x32_bf16 v[40:43], v[188:191], v[168:171], v[40:43]
	v_mfma_f32_16x16x32_bf16 v[44:47], v[196:199], v[168:171], v[44:47]
	v_mfma_f32_16x16x32_bf16 v[48:51], v[188:191], v[172:175], v[48:51]
	v_mfma_f32_16x16x32_bf16 v[52:55], v[196:199], v[172:175], v[52:55]
	v_mfma_f32_16x16x32_bf16 v[56:59], v[188:191], v[176:179], v[56:59]
	v_mfma_f32_16x16x32_bf16 v[60:63], v[196:199], v[176:179], v[60:63]
	ds_read_b128 v[164:167], v157 offset:24576
	ds_read_b128 v[168:171], v157 offset:26624
	ds_read_b128 v[172:175], v157 offset:28672
	ds_read_b128 v[176:179], v157 offset:30720
	ds_read_b128 v[180:183], v157 offset:32768
	s_waitcnt lgkmcnt(5)
	v_mfma_f32_16x16x32_bf16 v[64:67], v[188:191], v[136:139], v[64:67]
	v_mfma_f32_16x16x32_bf16 v[68:71], v[196:199], v[136:139], v[68:71]
	v_mfma_f32_16x16x32_bf16 v[72:75], v[188:191], v[140:143], v[72:75]
	v_mfma_f32_16x16x32_bf16 v[76:79], v[196:199], v[140:143], v[76:79]
	v_mfma_f32_16x16x32_bf16 v[80:83], v[188:191], v[144:147], v[80:83]
	v_mfma_f32_16x16x32_bf16 v[84:87], v[196:199], v[144:147], v[84:87]
	v_mfma_f32_16x16x32_bf16 v[88:91], v[188:191], v[148:151], v[88:91]
	v_mfma_f32_16x16x32_bf16 v[92:95], v[196:199], v[148:151], v[92:95]
	s_waitcnt vmcnt(0) lgkmcnt(0)
	s_barrier
	s_cmp_ge_u32 s63, 14
	s_cbranch_scc1 .Lg2_ff1_nd17_0
	s_add_u32 s56, s56, 0x80
	s_addc_u32 s57, s57, 0
	s_add_u32 m0, s62, 0x0
	s_add_u32 s4, s56, 0x0
	s_addc_u32 s5, s57, 0
	global_load_lds_dwordx4 v162, s[4:5]
	s_add_u32 m0, s62, 0x1000
	s_add_u32 s4, s56, 0x10000
	s_addc_u32 s5, s57, 0
	global_load_lds_dwordx4 v162, s[4:5]
	s_add_u32 m0, s62, 0x2000
	s_add_u32 s4, s56, 0x20000
	s_addc_u32 s5, s57, 0
	global_load_lds_dwordx4 v162, s[4:5]
	s_add_u32 m0, s62, 0x3000
	s_add_u32 s4, s56, 0x30000
	s_addc_u32 s5, s57, 0
	global_load_lds_dwordx4 v162, s[4:5]
	s_add_u32 m0, s62, 0x4000
	s_add_u32 s4, s56, 0x40000
	s_addc_u32 s5, s57, 0
	global_load_lds_dwordx4 v162, s[4:5]
	s_add_u32 m0, s62, 0x5000
	s_add_u32 s4, s56, 0x50000
	s_addc_u32 s5, s57, 0
	global_load_lds_dwordx4 v162, s[4:5]
	s_add_u32 m0, s62, 0x6000
	s_add_u32 s4, s56, 0x60000
	s_addc_u32 s5, s57, 0
	global_load_lds_dwordx4 v162, s[4:5]
	s_add_u32 m0, s62, 0x7000
	s_add_u32 s4, s56, 0x70000
	s_addc_u32 s5, s57, 0
	global_load_lds_dwordx4 v162, s[4:5]
	s_cmp_gt_u32 s70, 1
	s_cbranch_scc1 .Lg2_ff1_nodma_2
	s_add_u32 m0, s62, 0x8000
	s_add_u32 s4, s56, 0x80000
	s_addc_u32 s5, s57, 0
	global_load_lds_dwordx4 v162, s[4:5]

.Lg2_ff1_k16:
	s_add_u32 m0, s62, 0x0
	s_add_u32 s4, s56, 0x0
	s_addc_u32 s5, s57, 0
	global_load_lds_dwordx4 v162, s[4:5]
	s_add_u32 m0, s62, 0x1000
	s_add_u32 s4, s56, 0x10000
	s_addc_u32 s5, s57, 0
	global_load_lds_dwordx4 v162, s[4:5]
	s_add_u32 m0, s62, 0x2000
	s_add_u32 s4, s56, 0x20000
	s_addc_u32 s5, s57, 0
	global_load_lds_dwordx4 v162, s[4:5]
	s_add_u32 m0, s62, 0x3000
	s_add_u32 s4, s56, 0x30000
	s_addc_u32 s5, s57, 0
	global_load_lds_dwordx4 v162, s[4:5]
	s_add_u32 m0, s62, 0x4000
	s_add_u32 s4, s56, 0x40000
	s_addc_u32 s5, s57, 0
	global_load_lds_dwordx4 v162, s[4:5]
	s_add_u32 m0, s62, 0x5000
	s_add_u32 s4, s56, 0x50000
	s_addc_u32 s5, s57, 0
	global_load_lds_dwordx4 v162, s[4:5]
	s_add_u32 m0, s62, 0x6000
	s_add_u32 s4, s56, 0x60000
	s_addc_u32 s5, s57, 0
	global_load_lds_dwordx4 v162, s[4:5]
	s_add_u32 m0, s62, 0x7000
	s_add_u32 s4, s56, 0x70000
	s_addc_u32 s5, s57, 0
	global_load_lds_dwordx4 v162, s[4:5]
	global_load_dwordx4 v[184:187], v160, s[58:59] offset:0
	global_load_dwordx4 v[188:191], v160, s[58:59] offset:1024
	global_load_dwordx4 v[192:195], v161, s[58:59] offset:0
	global_load_dwordx4 v[196:199], v161, s[58:59] offset:1024
	s_add_u32 s56, s56, 0x80
	s_addc_u32 s57, s57, 0
	s_add_u32 m0, s62, 0x8800
	s_add_u32 s4, s56, 0x0
	s_addc_u32 s5, s57, 0
	global_load_lds_dwordx4 v162, s[4:5]
	s_add_u32 m0, s62, 0x9800
	s_add_u32 s4, s56, 0x10000
	s_addc_u32 s5, s57, 0
	global_load_lds_dwordx4 v162, s[4:5]
	s_add_u32 m0, s62, 0xa800
	s_add_u32 s4, s56, 0x20000
	s_addc_u32 s5, s57, 0
	global_load_lds_dwordx4 v162, s[4:5]
	s_add_u32 m0, s62, 0xb800
	s_add_u32 s4, s56, 0x30000
	s_addc_u32 s5, s57, 0
	global_load_lds_dwordx4 v162, s[4:5]
	s_add_u32 m0, s62, 0xc800
	s_add_u32 s4, s56, 0x40000
	s_addc_u32 s5, s57, 0
	global_load_lds_dwordx4 v162, s[4:5]
	s_add_u32 m0, s62, 0xd800
	s_add_u32 s4, s56, 0x50000
	s_addc_u32 s5, s57, 0
	global_load_lds_dwordx4 v162, s[4:5]
	s_add_u32 m0, s62, 0xe800
	s_add_u32 s4, s56, 0x60000
	s_addc_u32 s5, s57, 0
	global_load_lds_dwordx4 v162, s[4:5]
	s_add_u32 m0, s62, 0xf800
	s_add_u32 s4, s56, 0x70000
	s_addc_u32 s5, s57, 0
	global_load_lds_dwordx4 v162, s[4:5]
	s_add_u32 s58, s58, 0x800
	s_addc_u32 s59, s59, 0
	global_load_dwordx4 v[200:203], v160, s[58:59] offset:0
	global_load_dwordx4 v[204:207], v160, s[58:59] offset:1024
	global_load_dwordx4 v[208:211], v161, s[58:59] offset:0
	global_load_dwordx4 v[240:243], v161, s[58:59] offset:1024
	v_mov_b32_e32 v0, 0
	v_mov_b32_e32 v1, 0
	v_mov_b32_e32 v2, 0
	v_mov_b32_e32 v3, 0
	v_mov_b32_e32 v4, 0
	v_mov_b32_e32 v5, 0
	v_mov_b32_e32 v6, 0
	v_mov_b32_e32 v7, 0
	v_mov_b32_e32 v8, 0
	v_mov_b32_e32 v9, 0
	v_mov_b32_e32 v10, 0
	v_mov_b32_e32 v11, 0
	v_mov_b32_e32 v12, 0
	v_mov_b32_e32 v13, 0
	v_mov_b32_e32 v14, 0
	v_mov_b32_e32 v15, 0
	v_mov_b32_e32 v16, 0
	v_mov_b32_e32 v17, 0
	v_mov_b32_e32 v18, 0
	v_mov_b32_e32 v19, 0
	v_mov_b32_e32 v20, 0
	v_mov_b32_e32 v21, 0
	v_mov_b32_e32 v22, 0
	v_mov_b32_e32 v23, 0
	v_mov_b32_e32 v24, 0
	v_mov_b32_e32 v25, 0
	v_mov_b32_e32 v26, 0
	v_mov_b32_e32 v27, 0
	v_mov_b32_e32 v28, 0
	v_mov_b32_e32 v29, 0
	v_mov_b32_e32 v30, 0
	v_mov_b32_e32 v31, 0
	v_mov_b32_e32 v32, 0
	v_mov_b32_e32 v33, 0
	v_mov_b32_e32 v34, 0
	v_mov_b32_e32 v35, 0
	v_mov_b32_e32 v36, 0
	v_mov_b32_e32 v37, 0
	v_mov_b32_e32 v38, 0
	v_mov_b32_e32 v39, 0
	v_mov_b32_e32 v40, 0
	v_mov_b32_e32 v41, 0
	v_mov_b32_e32 v42, 0
	v_mov_b32_e32 v43, 0
	v_mov_b32_e32 v44, 0
	v_mov_b32_e32 v45, 0
	v_mov_b32_e32 v46, 0
	v_mov_b32_e32 v47, 0
	v_mov_b32_e32 v48, 0
	v_mov_b32_e32 v49, 0
	v_mov_b32_e32 v50, 0
	v_mov_b32_e32 v51, 0
	v_mov_b32_e32 v52, 0
	v_mov_b32_e32 v53, 0
	v_mov_b32_e32 v54, 0
	v_mov_b32_e32 v55, 0
	v_mov_b32_e32 v56, 0
	v_mov_b32_e32 v57, 0
	v_mov_b32_e32 v58, 0
	v_mov_b32_e32 v59, 0
	v_mov_b32_e32 v60, 0
	v_mov_b32_e32 v61, 0
	v_mov_b32_e32 v62, 0
	v_mov_b32_e32 v63, 0
	v_mov_b32_e32 v64, 0
	v_mov_b32_e32 v65, 0
	v_mov_b32_e32 v66, 0
	v_mov_b32_e32 v67, 0
	v_mov_b32_e32 v68, 0
	v_mov_b32_e32 v69, 0
	v_mov_b32_e32 v70, 0
	v_mov_b32_e32 v71, 0
	v_mov_b32_e32 v72, 0
	v_mov_b32_e32 v73, 0
	v_mov_b32_e32 v74, 0
	v_mov_b32_e32 v75, 0
	v_mov_b32_e32 v76, 0
	v_mov_b32_e32 v77, 0
	v_mov_b32_e32 v78, 0
	v_mov_b32_e32 v79, 0
	v_mov_b32_e32 v80, 0
	v_mov_b32_e32 v81, 0
	v_mov_b32_e32 v82, 0
	v_mov_b32_e32 v83, 0
	v_mov_b32_e32 v84, 0
	v_mov_b32_e32 v85, 0
	v_mov_b32_e32 v86, 0
	v_mov_b32_e32 v87, 0
	v_mov_b32_e32 v88, 0
	v_mov_b32_e32 v89, 0
	v_mov_b32_e32 v90, 0
	v_mov_b32_e32 v91, 0
	v_mov_b32_e32 v92, 0
	v_mov_b32_e32 v93, 0
	v_mov_b32_e32 v94, 0
	v_mov_b32_e32 v95, 0
	v_mov_b32_e32 v96, 0
	v_mov_b32_e32 v97, 0
	v_mov_b32_e32 v98, 0
	v_mov_b32_e32 v99, 0
	v_mov_b32_e32 v100, 0
	v_mov_b32_e32 v101, 0
	v_mov_b32_e32 v102, 0
	v_mov_b32_e32 v103, 0
	v_mov_b32_e32 v104, 0
	v_mov_b32_e32 v105, 0
	v_mov_b32_e32 v106, 0
	v_mov_b32_e32 v107, 0
	v_mov_b32_e32 v108, 0
	v_mov_b32_e32 v109, 0
	v_mov_b32_e32 v110, 0
	v_mov_b32_e32 v111, 0
	v_mov_b32_e32 v112, 0
	v_mov_b32_e32 v113, 0
	v_mov_b32_e32 v114, 0
	v_mov_b32_e32 v115, 0
	v_mov_b32_e32 v116, 0
	v_mov_b32_e32 v117, 0
	v_mov_b32_e32 v118, 0
	v_mov_b32_e32 v119, 0
	v_mov_b32_e32 v120, 0
	v_mov_b32_e32 v121, 0
	v_mov_b32_e32 v122, 0
	v_mov_b32_e32 v123, 0
	v_mov_b32_e32 v124, 0
	v_mov_b32_e32 v125, 0
	v_mov_b32_e32 v126, 0
	v_mov_b32_e32 v127, 0
	s_mov_b32 s63, 0
	s_waitcnt vmcnt(0)
	s_barrier
	ds_read_b128 v[136:139], v156 offset:0
	ds_read_b128 v[140:143], v156 offset:2048
	ds_read_b128 v[144:147], v156 offset:4096
	ds_read_b128 v[148:151], v156 offset:6144
	s_branch .Lg2_ff1_lin16

.Lg2_ff1_lin16:
	ds_read_b128 v[164:167], v156 offset:8192
	ds_read_b128 v[168:171], v156 offset:10240
	ds_read_b128 v[172:175], v156 offset:12288
	ds_read_b128 v[176:179], v156 offset:14336
	s_waitcnt lgkmcnt(4)
	v_mfma_f32_16x16x32_bf16 v[0:3], v[184:187], v[136:139], v[0:3]
	v_mfma_f32_16x16x32_bf16 v[4:7], v[192:195], v[136:139], v[4:7]
	v_mfma_f32_16x16x32_bf16 v[8:11], v[184:187], v[140:143], v[8:11]
	v_mfma_f32_16x16x32_bf16 v[12:15], v[192:195], v[140:143], v[12:15]
	v_mfma_f32_16x16x32_bf16 v[16:19], v[184:187], v[144:147], v[16:19]
	v_mfma_f32_16x16x32_bf16 v[20:23], v[192:195], v[144:147], v[20:23]
	v_mfma_f32_16x16x32_bf16 v[24:27], v[184:187], v[148:151], v[24:27]
	v_mfma_f32_16x16x32_bf16 v[28:31], v[192:195], v[148:151], v[28:31]
	ds_read_b128 v[136:139], v156 offset:16384
	ds_read_b128 v[140:143], v156 offset:18432
	ds_read_b128 v[144:147], v156 offset:20480
	ds_read_b128 v[148:151], v156 offset:22528
	s_waitcnt lgkmcnt(4)
	v_mfma_f32_16x16x32_bf16 v[32:35], v[184:187], v[164:167], v[32:35]
	v_mfma_f32_16x16x32_bf16 v[36:39], v[192:195], v[164:167], v[36:39]
	v_mfma_f32_16x16x32_bf16 v[40:43], v[184:187], v[168:171], v[40:43]
	v_mfma_f32_16x16x32_bf16 v[44:47], v[192:195], v[168:171], v[44:47]
	v_mfma_f32_16x16x32_bf16 v[48:51], v[184:187], v[172:175], v[48:51]
	v_mfma_f32_16x16x32_bf16 v[52:55], v[192:195], v[172:175], v[52:55]
	v_mfma_f32_16x16x32_bf16 v[56:59], v[184:187], v[176:179], v[56:59]
	v_mfma_f32_16x16x32_bf16 v[60:63], v[192:195], v[176:179], v[60:63]
	ds_read_b128 v[164:167], v156 offset:24576
	ds_read_b128 v[168:171], v156 offset:26624
	ds_read_b128 v[172:175], v156 offset:28672
	ds_read_b128 v[176:179], v156 offset:30720
	s_waitcnt lgkmcnt(4)
	v_mfma_f32_16x16x32_bf16 v[64:67], v[184:187], v[136:139], v[64:67]
	v_mfma_f32_16x16x32_bf16 v[68:71], v[192:195], v[136:139], v[68:71]
	v_mfma_f32_16x16x32_bf16 v[72:75], v[184:187], v[140:143], v[72:75]
	v_mfma_f32_16x16x32_bf16 v[76:79], v[192:195], v[140:143], v[76:79]
	v_mfma_f32_16x16x32_bf16 v[80:83], v[184:187], v[144:147], v[80:83]
	v_mfma_f32_16x16x32_bf16 v[84:87], v[192:195], v[144:147], v[84:87]
	v_mfma_f32_16x16x32_bf16 v[88:91], v[184:187], v[148:151], v[88:91]
	v_mfma_f32_16x16x32_bf16 v[92:95], v[192:195], v[148:151], v[92:95]
	ds_read_b128 v[136:139], v157 offset:0
	ds_read_b128 v[140:143], v157 offset:2048
	ds_read_b128 v[144:147], v157 offset:4096
	ds_read_b128 v[148:151], v157 offset:6144
	s_waitcnt lgkmcnt(4)
	v_mfma_f32_16x16x32_bf16 v[96:99], v[184:187], v[164:167], v[96:99]
	v_mfma_f32_16x16x32_bf16 v[100:103], v[192:195], v[164:167], v[100:103]
	v_mfma_f32_16x16x32_bf16 v[104:107], v[184:187], v[168:171], v[104:107]
	v_mfma_f32_16x16x32_bf16 v[108:111], v[192:195], v[168:171], v[108:111]
	v_mfma_f32_16x16x32_bf16 v[112:115], v[184:187], v[172:175], v[112:115]
	v_mfma_f32_16x16x32_bf16 v[116:119], v[192:195], v[172:175], v[116:119]
	v_mfma_f32_16x16x32_bf16 v[120:123], v[184:187], v[176:179], v[120:123]
	v_mfma_f32_16x16x32_bf16 v[124:127], v[192:195], v[176:179], v[124:127]
	ds_read_b128 v[164:167], v157 offset:8192
	ds_read_b128 v[168:171], v157 offset:10240
	ds_read_b128 v[172:175], v157 offset:12288
	ds_read_b128 v[176:179], v157 offset:14336
	s_waitcnt lgkmcnt(4)
	v_mfma_f32_16x16x32_bf16 v[0:3], v[188:191], v[136:139], v[0:3]
	v_mfma_f32_16x16x32_bf16 v[4:7], v[196:199], v[136:139], v[4:7]
	v_mfma_f32_16x16x32_bf16 v[8:11], v[188:191], v[140:143], v[8:11]
	v_mfma_f32_16x16x32_bf16 v[12:15], v[196:199], v[140:143], v[12:15]
	v_mfma_f32_16x16x32_bf16 v[16:19], v[188:191], v[144:147], v[16:19]
	v_mfma_f32_16x16x32_bf16 v[20:23], v[196:199], v[144:147], v[20:23]
	v_mfma_f32_16x16x32_bf16 v[24:27], v[188:191], v[148:151], v[24:27]
	v_mfma_f32_16x16x32_bf16 v[28:31], v[196:199], v[148:151], v[28:31]
	ds_read_b128 v[136:139], v157 offset:16384
	ds_read_b128 v[140:143], v157 offset:18432
	ds_read_b128 v[144:147], v157 offset:20480
	ds_read_b128 v[148:151], v157 offset:22528
	s_waitcnt lgkmcnt(4)
	v_mfma_f32_16x16x32_bf16 v[32:35], v[188:191], v[164:167], v[32:35]
	v_mfma_f32_16x16x32_bf16 v[36:39], v[196:199], v[164:167], v[36:39]
	v_mfma_f32_16x16x32_bf16 v[40:43], v[188:191], v[168:171], v[40:43]
	v_mfma_f32_16x16x32_bf16 v[44:47], v[196:199], v[168:171], v[44:47]
	v_mfma_f32_16x16x32_bf16 v[48:51], v[188:191], v[172:175], v[48:51]
	v_mfma_f32_16x16x32_bf16 v[52:55], v[196:199], v[172:175], v[52:55]
	v_mfma_f32_16x16x32_bf16 v[56:59], v[188:191], v[176:179], v[56:59]
	v_mfma_f32_16x16x32_bf16 v[60:63], v[196:199], v[176:179], v[60:63]
	ds_read_b128 v[164:167], v157 offset:24576
	ds_read_b128 v[168:171], v157 offset:26624
	ds_read_b128 v[172:175], v157 offset:28672
	ds_read_b128 v[176:179], v157 offset:30720
	s_waitcnt lgkmcnt(4)
	v_mfma_f32_16x16x32_bf16 v[64:67], v[188:191], v[136:139], v[64:67]
	v_mfma_f32_16x16x32_bf16 v[68:71], v[196:199], v[136:139], v[68:71]
	v_mfma_f32_16x16x32_bf16 v[72:75], v[188:191], v[140:143], v[72:75]
	v_mfma_f32_16x16x32_bf16 v[76:79], v[196:199], v[140:143], v[76:79]
	v_mfma_f32_16x16x32_bf16 v[80:83], v[188:191], v[144:147], v[80:83]
	v_mfma_f32_16x16x32_bf16 v[84:87], v[196:199], v[144:147], v[84:87]
	v_mfma_f32_16x16x32_bf16 v[88:91], v[188:191], v[148:151], v[88:91]
	v_mfma_f32_16x16x32_bf16 v[92:95], v[196:199], v[148:151], v[92:95]
	s_waitcnt vmcnt(0) lgkmcnt(0)
	s_barrier
	s_cmp_ge_u32 s63, 14
	s_cbranch_scc1 .Lg2_ff1_nd16_0
	s_add_u32 s56, s56, 0x80
	s_addc_u32 s57, s57, 0
	s_add_u32 m0, s62, 0x0
	s_add_u32 s4, s56, 0x0
	s_addc_u32 s5, s57, 0
	global_load_lds_dwordx4 v162, s[4:5]
	s_add_u32 m0, s62, 0x1000
	s_add_u32 s4, s56, 0x10000
	s_addc_u32 s5, s57, 0
	global_load_lds_dwordx4 v162, s[4:5]
	s_add_u32 m0, s62, 0x2000
	s_add_u32 s4, s56, 0x20000
	s_addc_u32 s5, s57, 0
	global_load_lds_dwordx4 v162, s[4:5]
	s_add_u32 m0, s62, 0x3000
	s_add_u32 s4, s56, 0x30000
	s_addc_u32 s5, s57, 0
	global_load_lds_dwordx4 v162, s[4:5]
	s_add_u32 m0, s62, 0x4000
	s_add_u32 s4, s56, 0x40000
	s_addc_u32 s5, s57, 0
	global_load_lds_dwordx4 v162, s[4:5]
	s_add_u32 m0, s62, 0x5000
	s_add_u32 s4, s56, 0x50000
	s_addc_u32 s5, s57, 0
	global_load_lds_dwordx4 v162, s[4:5]
	s_add_u32 m0, s62, 0x6000
	s_add_u32 s4, s56, 0x60000
	s_addc_u32 s5, s57, 0
	global_load_lds_dwordx4 v162, s[4:5]
	s_add_u32 m0, s62, 0x7000
	s_add_u32 s4, s56, 0x70000
	s_addc_u32 s5, s57, 0
	global_load_lds_dwordx4 v162, s[4:5]

.Lg2_up_lin17:
	ds_read_b128 v[164:167], v156 offset:8192
	ds_read_b128 v[168:171], v156 offset:10240
	ds_read_b128 v[172:175], v156 offset:12288
	ds_read_b128 v[176:179], v156 offset:14336
	s_waitcnt lgkmcnt(4)
	v_mfma_f32_16x16x32_bf16 v[0:3], v[184:187], v[136:139], v[0:3]
	v_mfma_f32_16x16x32_bf16 v[4:7], v[192:195], v[136:139], v[4:7]
	v_mfma_f32_16x16x32_bf16 v[8:11], v[184:187], v[140:143], v[8:11]
	v_mfma_f32_16x16x32_bf16 v[12:15], v[192:195], v[140:143], v[12:15]
	v_mfma_f32_16x16x32_bf16 v[16:19], v[184:187], v[144:147], v[16:19]
	v_mfma_f32_16x16x32_bf16 v[20:23], v[192:195], v[144:147], v[20:23]
	v_mfma_f32_16x16x32_bf16 v[24:27], v[184:187], v[148:151], v[24:27]
	v_mfma_f32_16x16x32_bf16 v[28:31], v[192:195], v[148:151], v[28:31]
	ds_read_b128 v[136:139], v156 offset:16384
	ds_read_b128 v[140:143], v156 offset:18432
	ds_read_b128 v[144:147], v156 offset:20480
	ds_read_b128 v[148:151], v156 offset:22528
	s_waitcnt lgkmcnt(4)
	v_mfma_f32_16x16x32_bf16 v[32:35], v[184:187], v[164:167], v[32:35]
	v_mfma_f32_16x16x32_bf16 v[36:39], v[192:195], v[164:167], v[36:39]
	v_mfma_f32_16x16x32_bf16 v[40:43], v[184:187], v[168:171], v[40:43]
	v_mfma_f32_16x16x32_bf16 v[44:47], v[192:195], v[168:171], v[44:47]
	v_mfma_f32_16x16x32_bf16 v[48:51], v[184:187], v[172:175], v[48:51]
	v_mfma_f32_16x16x32_bf16 v[52:55], v[192:195], v[172:175], v[52:55]
	v_mfma_f32_16x16x32_bf16 v[56:59], v[184:187], v[176:179], v[56:59]
	v_mfma_f32_16x16x32_bf16 v[60:63], v[192:195], v[176:179], v[60:63]
	ds_read_b128 v[164:167], v156 offset:24576
	ds_read_b128 v[168:171], v156 offset:26624
	ds_read_b128 v[172:175], v156 offset:28672
	ds_read_b128 v[176:179], v156 offset:30720
	ds_read_b128 v[180:183], v156 offset:32768
	s_waitcnt lgkmcnt(5)
	v_mfma_f32_16x16x32_bf16 v[64:67], v[184:187], v[136:139], v[64:67]
	v_mfma_f32_16x16x32_bf16 v[68:71], v[192:195], v[136:139], v[68:71]
	v_mfma_f32_16x16x32_bf16 v[72:75], v[184:187], v[140:143], v[72:75]
	v_mfma_f32_16x16x32_bf16 v[76:79], v[192:195], v[140:143], v[76:79]
	v_mfma_f32_16x16x32_bf16 v[80:83], v[184:187], v[144:147], v[80:83]
	v_mfma_f32_16x16x32_bf16 v[84:87], v[192:195], v[144:147], v[84:87]
	v_mfma_f32_16x16x32_bf16 v[88:91], v[184:187], v[148:151], v[88:91]
	v_mfma_f32_16x16x32_bf16 v[92:95], v[192:195], v[148:151], v[92:95]
	ds_read_b128 v[136:139], v157 offset:0
	ds_read_b128 v[140:143], v157 offset:2048
	ds_read_b128 v[144:147], v157 offset:4096
	ds_read_b128 v[148:151], v157 offset:6144
	s_waitcnt lgkmcnt(4)
	v_mfma_f32_16x16x32_bf16 v[96:99], v[184:187], v[164:167], v[96:99]
	v_mfma_f32_16x16x32_bf16 v[100:103], v[192:195], v[164:167], v[100:103]
	v_mfma_f32_16x16x32_bf16 v[104:107], v[184:187], v[168:171], v[104:107]
	v_mfma_f32_16x16x32_bf16 v[108:111], v[192:195], v[168:171], v[108:111]
	v_mfma_f32_16x16x32_bf16 v[112:115], v[184:187], v[172:175], v[112:115]
	v_mfma_f32_16x16x32_bf16 v[116:119], v[192:195], v[172:175], v[116:119]
	v_mfma_f32_16x16x32_bf16 v[120:123], v[184:187], v[176:179], v[120:123]
	v_mfma_f32_16x16x32_bf16 v[124:127], v[192:195], v[176:179], v[124:127]
	v_mfma_f32_16x16x32_bf16 v[128:131], v[184:187], v[180:183], v[128:131]
	v_mfma_f32_16x16x32_bf16 v[132:135], v[192:195], v[180:183], v[132:135]
	ds_read_b128 v[164:167], v157 offset:8192
	ds_read_b128 v[168:171], v157 offset:10240
	ds_read_b128 v[172:175], v157 offset:12288
	ds_read_b128 v[176:179], v157 offset:14336
	s_waitcnt lgkmcnt(4)
	v_mfma_f32_16x16x32_bf16 v[0:3], v[188:191], v[136:139], v[0:3]
	v_mfma_f32_16x16x32_bf16 v[4:7], v[196:199], v[136:139], v[4:7]
	v_mfma_f32_16x16x32_bf16 v[8:11], v[188:191], v[140:143], v[8:11]
	v_mfma_f32_16x16x32_bf16 v[12:15], v[196:199], v[140:143], v[12:15]
	v_mfma_f32_16x16x32_bf16 v[16:19], v[188:191], v[144:147], v[16:19]
	v_mfma_f32_16x16x32_bf16 v[20:23], v[196:199], v[144:147], v[20:23]
	v_mfma_f32_16x16x32_bf16 v[24:27], v[188:191], v[148:151], v[24:27]
	v_mfma_f32_16x16x32_bf16 v[28:31], v[196:199], v[148:151], v[28:31]
	ds_read_b128 v[136:139], v157 offset:16384
	ds_read_b128 v[140:143], v157 offset:18432
	ds_read_b128 v[144:147], v157 offset:20480
	ds_read_b128 v[148:151], v157 offset:22528
	s_waitcnt lgkmcnt(4)
	v_mfma_f32_16x16x32_bf16 v[32:35], v[188:191], v[164:167], v[32:35]
	v_mfma_f32_16x16x32_bf16 v[36:39], v[196:199], v[164:167], v[36:39]
	v_mfma_f32_16x16x32_bf16 v[40:43], v[188:191], v[168:171], v[40:43]
	v_mfma_f32_16x16x32_bf16 v[44:47], v[196:199], v[168:171], v[44:47]
	v_mfma_f32_16x16x32_bf16 v[48:51], v[188:191], v[172:175], v[48:51]
	v_mfma_f32_16x16x32_bf16 v[52:55], v[196:199], v[172:175], v[52:55]
	v_mfma_f32_16x16x32_bf16 v[56:59], v[188:191], v[176:179], v[56:59]
	v_mfma_f32_16x16x32_bf16 v[60:63], v[196:199], v[176:179], v[60:63]
	ds_read_b128 v[164:167], v157 offset:24576
	ds_read_b128 v[168:171], v157 offset:26624
	ds_read_b128 v[172:175], v157 offset:28672
	ds_read_b128 v[176:179], v157 offset:30720
	ds_read_b128 v[180:183], v157 offset:32768
	s_waitcnt lgkmcnt(5)
	v_mfma_f32_16x16x32_bf16 v[64:67], v[188:191], v[136:139], v[64:67]
	v_mfma_f32_16x16x32_bf16 v[68:71], v[196:199], v[136:139], v[68:71]
	v_mfma_f32_16x16x32_bf16 v[72:75], v[188:191], v[140:143], v[72:75]
	v_mfma_f32_16x16x32_bf16 v[76:79], v[196:199], v[140:143], v[76:79]
	v_mfma_f32_16x16x32_bf16 v[80:83], v[188:191], v[144:147], v[80:83]
	v_mfma_f32_16x16x32_bf16 v[84:87], v[196:199], v[144:147], v[84:87]
	v_mfma_f32_16x16x32_bf16 v[88:91], v[188:191], v[148:151], v[88:91]
	v_mfma_f32_16x16x32_bf16 v[92:95], v[196:199], v[148:151], v[92:95]
	s_waitcnt vmcnt(0) lgkmcnt(0)
	s_barrier
	s_cmp_ge_u32 s63, 2
	s_cbranch_scc1 .Lg2_up_nd17_0
	s_add_u32 s56, s56, 0x80
	s_addc_u32 s57, s57, 0
	s_add_u32 m0, s62, 0x0
	s_add_u32 s4, s56, 0x0
	s_addc_u32 s5, s57, 0
	global_load_lds_dwordx4 v162, s[4:5]
	s_add_u32 m0, s62, 0x1000
	s_add_u32 s4, s56, 0x72000
	s_addc_u32 s5, s57, 0
	global_load_lds_dwordx4 v162, s[4:5]
	s_add_u32 m0, s62, 0x2000
	s_add_u32 s4, s56, 0xe4000
	s_addc_u32 s5, s57, 0
	global_load_lds_dwordx4 v162, s[4:5]
	s_add_u32 m0, s62, 0x3000
	s_add_u32 s4, s56, 0x156000
	s_addc_u32 s5, s57, 0
	global_load_lds_dwordx4 v162, s[4:5]
	s_add_u32 m0, s62, 0x4000
	s_add_u32 s4, s56, 0x1c8000
	s_addc_u32 s5, s57, 0
	global_load_lds_dwordx4 v162, s[4:5]
	s_add_u32 m0, s62, 0x5000
	s_add_u32 s4, s56, 0x23a000
	s_addc_u32 s5, s57, 0
	global_load_lds_dwordx4 v162, s[4:5]
	s_add_u32 m0, s62, 0x6000
	s_add_u32 s4, s56, 0x2ac000
	s_addc_u32 s5, s57, 0
	global_load_lds_dwordx4 v162, s[4:5]
	s_add_u32 m0, s62, 0x7000
	s_add_u32 s4, s56, 0x31e000
	s_addc_u32 s5, s57, 0
	global_load_lds_dwordx4 v162, s[4:5]
	s_cmp_gt_u32 s70, 1
	s_cbranch_scc1 .Lg2_up_nodma_2
	s_add_u32 m0, s62, 0x8000
	s_add_u32 s4, s56, 0x390000
	s_addc_u32 s5, s57, 0
	global_load_lds_dwordx4 v162, s[4:5]

.Lg2_up_k16:
	s_add_u32 m0, s62, 0x0
	s_add_u32 s4, s56, 0x0
	s_addc_u32 s5, s57, 0
	global_load_lds_dwordx4 v162, s[4:5]
	s_add_u32 m0, s62, 0x1000
	s_add_u32 s4, s56, 0x72000
	s_addc_u32 s5, s57, 0
	global_load_lds_dwordx4 v162, s[4:5]
	s_add_u32 m0, s62, 0x2000
	s_add_u32 s4, s56, 0xe4000
	s_addc_u32 s5, s57, 0
	global_load_lds_dwordx4 v162, s[4:5]
	s_add_u32 m0, s62, 0x3000
	s_add_u32 s4, s56, 0x156000
	s_addc_u32 s5, s57, 0
	global_load_lds_dwordx4 v162, s[4:5]
	s_add_u32 m0, s62, 0x4000
	s_add_u32 s4, s56, 0x1c8000
	s_addc_u32 s5, s57, 0
	global_load_lds_dwordx4 v162, s[4:5]
	s_add_u32 m0, s62, 0x5000
	s_add_u32 s4, s56, 0x23a000
	s_addc_u32 s5, s57, 0
	global_load_lds_dwordx4 v162, s[4:5]
	s_add_u32 m0, s62, 0x6000
	s_add_u32 s4, s56, 0x2ac000
	s_addc_u32 s5, s57, 0
	global_load_lds_dwordx4 v162, s[4:5]
	s_add_u32 m0, s62, 0x7000
	s_add_u32 s4, s56, 0x31e000
	s_addc_u32 s5, s57, 0
	global_load_lds_dwordx4 v162, s[4:5]
	global_load_dwordx4 v[184:187], v160, s[58:59] offset:0
	global_load_dwordx4 v[188:191], v160, s[58:59] offset:1024
	global_load_dwordx4 v[192:195], v161, s[58:59] offset:0
	global_load_dwordx4 v[196:199], v161, s[58:59] offset:1024
	s_add_u32 s56, s56, 0x80
	s_addc_u32 s57, s57, 0
	s_add_u32 m0, s62, 0x8800
	s_add_u32 s4, s56, 0x0
	s_addc_u32 s5, s57, 0
	global_load_lds_dwordx4 v162, s[4:5]
	s_add_u32 m0, s62, 0x9800
	s_add_u32 s4, s56, 0x72000
	s_addc_u32 s5, s57, 0
	global_load_lds_dwordx4 v162, s[4:5]
	s_add_u32 m0, s62, 0xa800
	s_add_u32 s4, s56, 0xe4000
	s_addc_u32 s5, s57, 0
	global_load_lds_dwordx4 v162, s[4:5]
	s_add_u32 m0, s62, 0xb800
	s_add_u32 s4, s56, 0x156000
	s_addc_u32 s5, s57, 0
	global_load_lds_dwordx4 v162, s[4:5]
	s_add_u32 m0, s62, 0xc800
	s_add_u32 s4, s56, 0x1c8000
	s_addc_u32 s5, s57, 0
	global_load_lds_dwordx4 v162, s[4:5]
	s_add_u32 m0, s62, 0xd800
	s_add_u32 s4, s56, 0x23a000
	s_addc_u32 s5, s57, 0
	global_load_lds_dwordx4 v162, s[4:5]
	s_add_u32 m0, s62, 0xe800
	s_add_u32 s4, s56, 0x2ac000
	s_addc_u32 s5, s57, 0
	global_load_lds_dwordx4 v162, s[4:5]
	s_add_u32 m0, s62, 0xf800
	s_add_u32 s4, s56, 0x31e000
	s_addc_u32 s5, s57, 0
	global_load_lds_dwordx4 v162, s[4:5]
	s_add_u32 s58, s58, 0x800
	s_addc_u32 s59, s59, 0
	global_load_dwordx4 v[200:203], v160, s[58:59] offset:0
	global_load_dwordx4 v[204:207], v160, s[58:59] offset:1024
	global_load_dwordx4 v[208:211], v161, s[58:59] offset:0
	global_load_dwordx4 v[240:243], v161, s[58:59] offset:1024
	v_mov_b32_e32 v0, 0
	v_mov_b32_e32 v1, 0
	v_mov_b32_e32 v2, 0
	v_mov_b32_e32 v3, 0
	v_mov_b32_e32 v4, 0
	v_mov_b32_e32 v5, 0
	v_mov_b32_e32 v6, 0
	v_mov_b32_e32 v7, 0
	v_mov_b32_e32 v8, 0
	v_mov_b32_e32 v9, 0
	v_mov_b32_e32 v10, 0
	v_mov_b32_e32 v11, 0
	v_mov_b32_e32 v12, 0
	v_mov_b32_e32 v13, 0
	v_mov_b32_e32 v14, 0
	v_mov_b32_e32 v15, 0
	v_mov_b32_e32 v16, 0
	v_mov_b32_e32 v17, 0
	v_mov_b32_e32 v18, 0
	v_mov_b32_e32 v19, 0
	v_mov_b32_e32 v20, 0
	v_mov_b32_e32 v21, 0
	v_mov_b32_e32 v22, 0
	v_mov_b32_e32 v23, 0
	v_mov_b32_e32 v24, 0
	v_mov_b32_e32 v25, 0
	v_mov_b32_e32 v26, 0
	v_mov_b32_e32 v27, 0
	v_mov_b32_e32 v28, 0
	v_mov_b32_e32 v29, 0
	v_mov_b32_e32 v30, 0
	v_mov_b32_e32 v31, 0
	v_mov_b32_e32 v32, 0
	v_mov_b32_e32 v33, 0
	v_mov_b32_e32 v34, 0
	v_mov_b32_e32 v35, 0
	v_mov_b32_e32 v36, 0
	v_mov_b32_e32 v37, 0
	v_mov_b32_e32 v38, 0
	v_mov_b32_e32 v39, 0
	v_mov_b32_e32 v40, 0
	v_mov_b32_e32 v41, 0
	v_mov_b32_e32 v42, 0
	v_mov_b32_e32 v43, 0
	v_mov_b32_e32 v44, 0
	v_mov_b32_e32 v45, 0
	v_mov_b32_e32 v46, 0
	v_mov_b32_e32 v47, 0
	v_mov_b32_e32 v48, 0
	v_mov_b32_e32 v49, 0
	v_mov_b32_e32 v50, 0
	v_mov_b32_e32 v51, 0
	v_mov_b32_e32 v52, 0
	v_mov_b32_e32 v53, 0
	v_mov_b32_e32 v54, 0
	v_mov_b32_e32 v55, 0
	v_mov_b32_e32 v56, 0
	v_mov_b32_e32 v57, 0
	v_mov_b32_e32 v58, 0
	v_mov_b32_e32 v59, 0
	v_mov_b32_e32 v60, 0
	v_mov_b32_e32 v61, 0
	v_mov_b32_e32 v62, 0
	v_mov_b32_e32 v63, 0
	v_mov_b32_e32 v64, 0
	v_mov_b32_e32 v65, 0
	v_mov_b32_e32 v66, 0
	v_mov_b32_e32 v67, 0
	v_mov_b32_e32 v68, 0
	v_mov_b32_e32 v69, 0
	v_mov_b32_e32 v70, 0
	v_mov_b32_e32 v71, 0
	v_mov_b32_e32 v72, 0
	v_mov_b32_e32 v73, 0
	v_mov_b32_e32 v74, 0
	v_mov_b32_e32 v75, 0
	v_mov_b32_e32 v76, 0
	v_mov_b32_e32 v77, 0
	v_mov_b32_e32 v78, 0
	v_mov_b32_e32 v79, 0
	v_mov_b32_e32 v80, 0
	v_mov_b32_e32 v81, 0
	v_mov_b32_e32 v82, 0
	v_mov_b32_e32 v83, 0
	v_mov_b32_e32 v84, 0
	v_mov_b32_e32 v85, 0
	v_mov_b32_e32 v86, 0
	v_mov_b32_e32 v87, 0
	v_mov_b32_e32 v88, 0
	v_mov_b32_e32 v89, 0
	v_mov_b32_e32 v90, 0
	v_mov_b32_e32 v91, 0
	v_mov_b32_e32 v92, 0
	v_mov_b32_e32 v93, 0
	v_mov_b32_e32 v94, 0
	v_mov_b32_e32 v95, 0
	v_mov_b32_e32 v96, 0
	v_mov_b32_e32 v97, 0
	v_mov_b32_e32 v98, 0
	v_mov_b32_e32 v99, 0
	v_mov_b32_e32 v100, 0
	v_mov_b32_e32 v101, 0
	v_mov_b32_e32 v102, 0
	v_mov_b32_e32 v103, 0
	v_mov_b32_e32 v104, 0
	v_mov_b32_e32 v105, 0
	v_mov_b32_e32 v106, 0
	v_mov_b32_e32 v107, 0
	v_mov_b32_e32 v108, 0
	v_mov_b32_e32 v109, 0
	v_mov_b32_e32 v110, 0
	v_mov_b32_e32 v111, 0
	v_mov_b32_e32 v112, 0
	v_mov_b32_e32 v113, 0
	v_mov_b32_e32 v114, 0
	v_mov_b32_e32 v115, 0
	v_mov_b32_e32 v116, 0
	v_mov_b32_e32 v117, 0
	v_mov_b32_e32 v118, 0
	v_mov_b32_e32 v119, 0
	v_mov_b32_e32 v120, 0
	v_mov_b32_e32 v121, 0
	v_mov_b32_e32 v122, 0
	v_mov_b32_e32 v123, 0
	v_mov_b32_e32 v124, 0
	v_mov_b32_e32 v125, 0
	v_mov_b32_e32 v126, 0
	v_mov_b32_e32 v127, 0
	s_mov_b32 s63, 0
	s_waitcnt vmcnt(0)
	s_barrier
	ds_read_b128 v[136:139], v156 offset:0
	ds_read_b128 v[140:143], v156 offset:2048
	ds_read_b128 v[144:147], v156 offset:4096
	ds_read_b128 v[148:151], v156 offset:6144
	s_branch .Lg2_up_lin16

.Lg2_up_lin16:
	ds_read_b128 v[164:167], v156 offset:8192
	ds_read_b128 v[168:171], v156 offset:10240
	ds_read_b128 v[172:175], v156 offset:12288
	ds_read_b128 v[176:179], v156 offset:14336
	s_waitcnt lgkmcnt(4)
	v_mfma_f32_16x16x32_bf16 v[0:3], v[184:187], v[136:139], v[0:3]
	v_mfma_f32_16x16x32_bf16 v[4:7], v[192:195], v[136:139], v[4:7]
	v_mfma_f32_16x16x32_bf16 v[8:11], v[184:187], v[140:143], v[8:11]
	v_mfma_f32_16x16x32_bf16 v[12:15], v[192:195], v[140:143], v[12:15]
	v_mfma_f32_16x16x32_bf16 v[16:19], v[184:187], v[144:147], v[16:19]
	v_mfma_f32_16x16x32_bf16 v[20:23], v[192:195], v[144:147], v[20:23]
	v_mfma_f32_16x16x32_bf16 v[24:27], v[184:187], v[148:151], v[24:27]
	v_mfma_f32_16x16x32_bf16 v[28:31], v[192:195], v[148:151], v[28:31]
	ds_read_b128 v[136:139], v156 offset:16384
	ds_read_b128 v[140:143], v156 offset:18432
	ds_read_b128 v[144:147], v156 offset:20480
	ds_read_b128 v[148:151], v156 offset:22528
	s_waitcnt lgkmcnt(4)
	v_mfma_f32_16x16x32_bf16 v[32:35], v[184:187], v[164:167], v[32:35]
	v_mfma_f32_16x16x32_bf16 v[36:39], v[192:195], v[164:167], v[36:39]
	v_mfma_f32_16x16x32_bf16 v[40:43], v[184:187], v[168:171], v[40:43]
	v_mfma_f32_16x16x32_bf16 v[44:47], v[192:195], v[168:171], v[44:47]
	v_mfma_f32_16x16x32_bf16 v[48:51], v[184:187], v[172:175], v[48:51]
	v_mfma_f32_16x16x32_bf16 v[52:55], v[192:195], v[172:175], v[52:55]
	v_mfma_f32_16x16x32_bf16 v[56:59], v[184:187], v[176:179], v[56:59]
	v_mfma_f32_16x16x32_bf16 v[60:63], v[192:195], v[176:179], v[60:63]
	ds_read_b128 v[164:167], v156 offset:24576
	ds_read_b128 v[168:171], v156 offset:26624
	ds_read_b128 v[172:175], v156 offset:28672
	ds_read_b128 v[176:179], v156 offset:30720
	s_waitcnt lgkmcnt(4)
	v_mfma_f32_16x16x32_bf16 v[64:67], v[184:187], v[136:139], v[64:67]
	v_mfma_f32_16x16x32_bf16 v[68:71], v[192:195], v[136:139], v[68:71]
	v_mfma_f32_16x16x32_bf16 v[72:75], v[184:187], v[140:143], v[72:75]
	v_mfma_f32_16x16x32_bf16 v[76:79], v[192:195], v[140:143], v[76:79]
	v_mfma_f32_16x16x32_bf16 v[80:83], v[184:187], v[144:147], v[80:83]
	v_mfma_f32_16x16x32_bf16 v[84:87], v[192:195], v[144:147], v[84:87]
	v_mfma_f32_16x16x32_bf16 v[88:91], v[184:187], v[148:151], v[88:91]
	v_mfma_f32_16x16x32_bf16 v[92:95], v[192:195], v[148:151], v[92:95]
	ds_read_b128 v[136:139], v157 offset:0
	ds_read_b128 v[140:143], v157 offset:2048
	ds_read_b128 v[144:147], v157 offset:4096
	ds_read_b128 v[148:151], v157 offset:6144
	s_waitcnt lgkmcnt(4)
	v_mfma_f32_16x16x32_bf16 v[96:99], v[184:187], v[164:167], v[96:99]
	v_mfma_f32_16x16x32_bf16 v[100:103], v[192:195], v[164:167], v[100:103]
	v_mfma_f32_16x16x32_bf16 v[104:107], v[184:187], v[168:171], v[104:107]
	v_mfma_f32_16x16x32_bf16 v[108:111], v[192:195], v[168:171], v[108:111]
	v_mfma_f32_16x16x32_bf16 v[112:115], v[184:187], v[172:175], v[112:115]
	v_mfma_f32_16x16x32_bf16 v[116:119], v[192:195], v[172:175], v[116:119]
	v_mfma_f32_16x16x32_bf16 v[120:123], v[184:187], v[176:179], v[120:123]
	v_mfma_f32_16x16x32_bf16 v[124:127], v[192:195], v[176:179], v[124:127]
	ds_read_b128 v[164:167], v157 offset:8192
	ds_read_b128 v[168:171], v157 offset:10240
	ds_read_b128 v[172:175], v157 offset:12288
	ds_read_b128 v[176:179], v157 offset:14336
	s_waitcnt lgkmcnt(4)
	v_mfma_f32_16x16x32_bf16 v[0:3], v[188:191], v[136:139], v[0:3]
	v_mfma_f32_16x16x32_bf16 v[4:7], v[196:199], v[136:139], v[4:7]
	v_mfma_f32_16x16x32_bf16 v[8:11], v[188:191], v[140:143], v[8:11]
	v_mfma_f32_16x16x32_bf16 v[12:15], v[196:199], v[140:143], v[12:15]
	v_mfma_f32_16x16x32_bf16 v[16:19], v[188:191], v[144:147], v[16:19]
	v_mfma_f32_16x16x32_bf16 v[20:23], v[196:199], v[144:147], v[20:23]
	v_mfma_f32_16x16x32_bf16 v[24:27], v[188:191], v[148:151], v[24:27]
	v_mfma_f32_16x16x32_bf16 v[28:31], v[196:199], v[148:151], v[28:31]
	ds_read_b128 v[136:139], v157 offset:16384
	ds_read_b128 v[140:143], v157 offset:18432
	ds_read_b128 v[144:147], v157 offset:20480
	ds_read_b128 v[148:151], v157 offset:22528
	s_waitcnt lgkmcnt(4)
	v_mfma_f32_16x16x32_bf16 v[32:35], v[188:191], v[164:167], v[32:35]
	v_mfma_f32_16x16x32_bf16 v[36:39], v[196:199], v[164:167], v[36:39]
	v_mfma_f32_16x16x32_bf16 v[40:43], v[188:191], v[168:171], v[40:43]
	v_mfma_f32_16x16x32_bf16 v[44:47], v[196:199], v[168:171], v[44:47]
	v_mfma_f32_16x16x32_bf16 v[48:51], v[188:191], v[172:175], v[48:51]
	v_mfma_f32_16x16x32_bf16 v[52:55], v[196:199], v[172:175], v[52:55]
	v_mfma_f32_16x16x32_bf16 v[56:59], v[188:191], v[176:179], v[56:59]
	v_mfma_f32_16x16x32_bf16 v[60:63], v[196:199], v[176:179], v[60:63]
	ds_read_b128 v[164:167], v157 offset:24576
	ds_read_b128 v[168:171], v157 offset:26624
	ds_read_b128 v[172:175], v157 offset:28672
	ds_read_b128 v[176:179], v157 offset:30720
	s_waitcnt lgkmcnt(4)
	v_mfma_f32_16x16x32_bf16 v[64:67], v[188:191], v[136:139], v[64:67]
	v_mfma_f32_16x16x32_bf16 v[68:71], v[196:199], v[136:139], v[68:71]
	v_mfma_f32_16x16x32_bf16 v[72:75], v[188:191], v[140:143], v[72:75]
	v_mfma_f32_16x16x32_bf16 v[76:79], v[196:199], v[140:143], v[76:79]
	v_mfma_f32_16x16x32_bf16 v[80:83], v[188:191], v[144:147], v[80:83]
	v_mfma_f32_16x16x32_bf16 v[84:87], v[196:199], v[144:147], v[84:87]
	v_mfma_f32_16x16x32_bf16 v[88:91], v[188:191], v[148:151], v[88:91]
	v_mfma_f32_16x16x32_bf16 v[92:95], v[196:199], v[148:151], v[92:95]
	s_waitcnt vmcnt(0) lgkmcnt(0)
	s_barrier
	s_cmp_ge_u32 s63, 2
	s_cbranch_scc1 .Lg2_up_nd16_0
	s_add_u32 s56, s56, 0x80
	s_addc_u32 s57, s57, 0
	s_add_u32 m0, s62, 0x0
	s_add_u32 s4, s56, 0x0
	s_addc_u32 s5, s57, 0
	global_load_lds_dwordx4 v162, s[4:5]
	s_add_u32 m0, s62, 0x1000
	s_add_u32 s4, s56, 0x72000
	s_addc_u32 s5, s57, 0
	global_load_lds_dwordx4 v162, s[4:5]
	s_add_u32 m0, s62, 0x2000
	s_add_u32 s4, s56, 0xe4000
	s_addc_u32 s5, s57, 0
	global_load_lds_dwordx4 v162, s[4:5]
	s_add_u32 m0, s62, 0x3000
	s_add_u32 s4, s56, 0x156000
	s_addc_u32 s5, s57, 0
	global_load_lds_dwordx4 v162, s[4:5]
	s_add_u32 m0, s62, 0x4000
	s_add_u32 s4, s56, 0x1c8000
	s_addc_u32 s5, s57, 0
	global_load_lds_dwordx4 v162, s[4:5]
	s_add_u32 m0, s62, 0x5000
	s_add_u32 s4, s56, 0x23a000
	s_addc_u32 s5, s57, 0
	global_load_lds_dwordx4 v162, s[4:5]
	s_add_u32 m0, s62, 0x6000
	s_add_u32 s4, s56, 0x2ac000
	s_addc_u32 s5, s57, 0
	global_load_lds_dwordx4 v162, s[4:5]
	s_add_u32 m0, s62, 0x7000
	s_add_u32 s4, s56, 0x31e000
	s_addc_u32 s5, s57, 0
	global_load_lds_dwordx4 v162, s[4:5]
